# lazy softmax reference threshold 40 -> 64 log2 units (p <= 2^64, exact): fewer reference updates in the FoX prompt job
# speedup vs baseline: 1.0099x; 1.0093x over previous
.Lj3ld_norka:
	s_or_b64 exec, exec, s[6:7]
	s_waitcnt lgkmcnt(0)
	v_mfma_f32_32x32x16_bf16 v[130:145], v[232:235], v[236:239], v[130:145]
	s_nop 11
	v_mov_b32_e32 v146, v130
	v_mov_b32_e32 v147, v131
	v_max3_f32 v130, v146, v147, v132
	v_max3_f32 v131, v139, v140, v141
	v_max3_f32 v130, v130, v133, v134
	v_max3_f32 v131, v131, v142, v143
	v_max3_f32 v130, v130, v135, v136
	v_max3_f32 v131, v131, v144, v145
	v_max3_f32 v130, v130, v137, v138
	v_max_f32_e32 v130, v130, v131
	v_sub_f32_e32 v131, v230, v130
	v_cmp_gt_f32_e32 vcc, 0xc2800000, v131
	s_cbranch_vccnz .Llazy0_full
	ds_read_b64_tr_b16 v[232:233], v222
	ds_read_b64_tr_b16 v[234:235], v222 offset:4736
	ds_read_b64_tr_b16 v[236:237], v222 offset:64
	ds_read_b64_tr_b16 v[238:239], v222 offset:4800
	ds_read_b64_tr_b16 v[240:241], v222 offset:128
	ds_read_b64_tr_b16 v[242:243], v222 offset:4864
	ds_read_b64_tr_b16 v[246:247], v222 offset:192
	ds_read_b64_tr_b16 v[248:249], v222 offset:4928
	v_mov_b32_e32 v229, v230
	v_mov_b32_e32 v130, 1.0
	s_branch .LBB0_946

.LBB0_954:
	s_or_b64 exec, exec, s[10:11]
	s_cmp_gt_i32 s40, 5
	v_add_u32_e32 v182, v224, v198
	s_cbranch_scc1 .LBB0_958
	ds_read_b128 v[130:133], v182
	ds_read_b128 v[134:137], v223
	ds_read_b128 v[146:149], v182 offset:32
	ds_read_b128 v[150:153], v223 offset:1024
	ds_read_b128 v[184:187], v182 offset:64
	ds_read_b128 v[188:191], v223 offset:2048
	s_waitcnt lgkmcnt(4)
	v_mfma_f32_32x32x16_bf16 v[130:145], v[130:133], v[134:137], 0
	s_waitcnt lgkmcnt(2)
	v_mfma_f32_32x32x16_bf16 v[146:161], v[146:149], v[150:153], 0
	s_waitcnt lgkmcnt(0)
	v_mfma_f32_32x32x16_bf16 v[130:145], v[184:187], v[188:191], v[130:145]
	ds_read_b128 v[184:187], v182 offset:96
	ds_read_b128 v[188:191], v223 offset:3072
	s_waitcnt lgkmcnt(0)
	v_mfma_f32_32x32x16_bf16 v[146:161], v[184:187], v[188:191], v[146:161]
	ds_read_b128 v[184:187], v182 offset:128
	ds_read_b128 v[188:191], v223 offset:4096
	s_waitcnt lgkmcnt(0)
	v_mfma_f32_32x32x16_bf16 v[130:145], v[184:187], v[188:191], v[130:145]
	ds_read_b128 v[184:187], v182 offset:160
	ds_read_b128 v[188:191], v223 offset:5120
	s_waitcnt lgkmcnt(0)
	v_mfma_f32_32x32x16_bf16 v[146:161], v[184:187], v[188:191], v[146:161]
	ds_read_b128 v[184:187], v182 offset:192
	ds_read_b128 v[188:191], v223 offset:6144
	s_waitcnt lgkmcnt(0)
	v_mfma_f32_32x32x16_bf16 v[130:145], v[184:187], v[188:191], v[130:145]
	ds_read_b128 v[184:187], v182 offset:224
	ds_read_b128 v[188:191], v223 offset:7168
	s_waitcnt lgkmcnt(0)
	v_mfma_f32_32x32x16_bf16 v[146:161], v[184:187], v[188:191], v[146:161]
	ds_read_b128 v[184:187], v182 offset:256
	ds_read_b128 v[188:191], v223 offset:8192
	s_waitcnt lgkmcnt(0)
	v_mfma_f32_32x32x16_bf16 v[130:145], v[184:187], v[188:191], v[130:145]
	ds_read_b128 v[184:187], v182 offset:288
	ds_read_b128 v[188:191], v223 offset:9216
	s_waitcnt lgkmcnt(0)
	v_mfma_f32_32x32x16_bf16 v[146:161], v[184:187], v[188:191], v[146:161]
	ds_read_b128 v[184:187], v182 offset:320
	ds_read_b128 v[188:191], v223 offset:10240
	s_waitcnt lgkmcnt(0)
	v_mfma_f32_32x32x16_bf16 v[130:145], v[184:187], v[188:191], v[130:145]
	ds_read_b128 v[184:187], v182 offset:352
	ds_read_b128 v[188:191], v223 offset:11264
	s_waitcnt lgkmcnt(0)
	v_mfma_f32_32x32x16_bf16 v[146:161], v[184:187], v[188:191], v[146:161]
	ds_read_b128 v[184:187], v182 offset:384
	ds_read_b128 v[188:191], v223 offset:12288
	s_waitcnt lgkmcnt(0)
	v_mfma_f32_32x32x16_bf16 v[130:145], v[184:187], v[188:191], v[130:145]
	ds_read_b128 v[184:187], v182 offset:416
	ds_read_b128 v[188:191], v223 offset:13312
	s_waitcnt lgkmcnt(0)
	v_mfma_f32_32x32x16_bf16 v[146:161], v[184:187], v[188:191], v[146:161]
	ds_read_b128 v[184:187], v182 offset:448
	ds_read_b128 v[188:191], v223 offset:14336
	s_waitcnt lgkmcnt(0)
	v_mfma_f32_32x32x16_bf16 v[130:145], v[184:187], v[188:191], v[130:145]
	ds_read_b128 v[184:187], v182 offset:480
	ds_read_b128 v[188:191], v223 offset:15360
	s_waitcnt lgkmcnt(0)
	v_mfma_f32_32x32x16_bf16 v[146:161], v[184:187], v[188:191], v[146:161]
	ds_read_b128 v[184:187], v182 offset:512
	ds_read_b128 v[188:191], v223 offset:16384
	s_waitcnt lgkmcnt(0)
	v_mfma_f32_32x32x16_bf16 v[130:145], v[184:187], v[188:191], v[130:145]
	ds_read_b128 v[184:187], v182 offset:544
	ds_read_b128 v[188:191], v223 offset:17408
	s_waitcnt lgkmcnt(0)
	v_mfma_f32_32x32x16_bf16 v[146:161], v[184:187], v[188:191], v[146:161]
	s_nop 11
	v_pk_add_f32 v[146:147], v[130:131], v[146:147]
	v_pk_add_f32 v[132:133], v[132:133], v[148:149]
	v_max_f32_e32 v130, v146, v147
	v_pk_add_f32 v[134:135], v[134:135], v[150:151]
	v_max3_f32 v130, v130, v132, v133
	v_pk_add_f32 v[136:137], v[136:137], v[152:153]
	v_max3_f32 v130, v130, v134, v135
	v_mbcnt_hi_u32_b32 v131, -1, v217
	v_pk_add_f32 v[138:139], v[138:139], v[154:155]
	v_max3_f32 v130, v130, v136, v137
	v_and_b32_e32 v149, 64, v131
	v_pk_add_f32 v[140:141], v[140:141], v[156:157]
	v_max3_f32 v130, v130, v138, v139
	v_xor_b32_e32 v148, 32, v131
	v_add_u32_e32 v149, 64, v149
	v_pk_add_f32 v[142:143], v[142:143], v[158:159]
	v_max3_f32 v130, v130, v140, v141
	v_cmp_lt_i32_e32 vcc, v148, v149
	v_pk_add_f32 v[144:145], v[144:145], v[160:161]
	v_max3_f32 v130, v130, v142, v143
	v_cndmask_b32_e32 v131, v131, v148, vcc
	v_max3_f32 v130, v130, v144, v145
	v_lshlrev_b32_e32 v131, 2, v131
	ds_bpermute_b32 v131, v131, v130
	s_waitcnt lgkmcnt(0)
	v_max3_f32 v184, v229, v130, v131
	v_sub_f32_e32 v130, v229, v184
	v_cmp_gt_f32_e32 vcc, 0xc2800000, v130
	s_cbranch_vccnz .Llazy1_full
	v_mov_b32_e32 v184, v229
	v_mov_b32_e32 v130, 1.0
	s_branch .LBB0_957

.LBB0_963:
	s_andn2_b64 vcc, exec, s[6:7]
	s_cbranch_vccnz .LBB0_967
	ds_read_b128 v[130:133], v182
	ds_read_b128 v[134:137], v223
	ds_read_b128 v[146:149], v182 offset:32
	ds_read_b128 v[150:153], v223 offset:1024
	ds_read_b128 v[162:165], v182 offset:64
	ds_read_b128 v[166:169], v223 offset:2048
	s_waitcnt lgkmcnt(4)
	v_mfma_f32_32x32x16_bf16 v[130:145], v[130:133], v[134:137], 0
	s_waitcnt lgkmcnt(2)
	v_mfma_f32_32x32x16_bf16 v[146:161], v[146:149], v[150:153], 0
	s_waitcnt lgkmcnt(0)
	v_mfma_f32_32x32x16_bf16 v[130:145], v[162:165], v[166:169], v[130:145]
	ds_read_b128 v[162:165], v182 offset:96
	ds_read_b128 v[166:169], v223 offset:3072
	s_waitcnt lgkmcnt(0)
	v_mfma_f32_32x32x16_bf16 v[146:161], v[162:165], v[166:169], v[146:161]
	ds_read_b128 v[162:165], v182 offset:128
	ds_read_b128 v[166:169], v223 offset:4096
	s_waitcnt lgkmcnt(0)
	v_mfma_f32_32x32x16_bf16 v[130:145], v[162:165], v[166:169], v[130:145]
	ds_read_b128 v[162:165], v182 offset:160
	ds_read_b128 v[166:169], v223 offset:5120
	s_waitcnt lgkmcnt(0)
	v_mfma_f32_32x32x16_bf16 v[146:161], v[162:165], v[166:169], v[146:161]
	ds_read_b128 v[162:165], v182 offset:192
	ds_read_b128 v[166:169], v223 offset:6144
	s_waitcnt lgkmcnt(0)
	v_mfma_f32_32x32x16_bf16 v[130:145], v[162:165], v[166:169], v[130:145]
	ds_read_b128 v[162:165], v182 offset:224
	ds_read_b128 v[166:169], v223 offset:7168
	s_waitcnt lgkmcnt(0)
	v_mfma_f32_32x32x16_bf16 v[146:161], v[162:165], v[166:169], v[146:161]
	ds_read_b128 v[162:165], v182 offset:256
	ds_read_b128 v[166:169], v223 offset:8192
	s_waitcnt lgkmcnt(0)
	v_mfma_f32_32x32x16_bf16 v[130:145], v[162:165], v[166:169], v[130:145]
	ds_read_b128 v[162:165], v182 offset:288
	ds_read_b128 v[166:169], v223 offset:9216
	s_waitcnt lgkmcnt(0)
	v_mfma_f32_32x32x16_bf16 v[146:161], v[162:165], v[166:169], v[146:161]
	ds_read_b128 v[162:165], v182 offset:320
	ds_read_b128 v[166:169], v223 offset:10240
	s_waitcnt lgkmcnt(0)
	v_mfma_f32_32x32x16_bf16 v[130:145], v[162:165], v[166:169], v[130:145]
	ds_read_b128 v[162:165], v182 offset:352
	ds_read_b128 v[166:169], v223 offset:11264
	s_waitcnt lgkmcnt(0)
	v_mfma_f32_32x32x16_bf16 v[146:161], v[162:165], v[166:169], v[146:161]
	ds_read_b128 v[162:165], v182 offset:384
	ds_read_b128 v[166:169], v223 offset:12288
	s_waitcnt lgkmcnt(0)
	v_mfma_f32_32x32x16_bf16 v[130:145], v[162:165], v[166:169], v[130:145]
	ds_read_b128 v[162:165], v182 offset:416
	ds_read_b128 v[166:169], v223 offset:13312
	s_waitcnt lgkmcnt(0)
	v_mfma_f32_32x32x16_bf16 v[146:161], v[162:165], v[166:169], v[146:161]
	ds_read_b128 v[162:165], v182 offset:448
	ds_read_b128 v[166:169], v223 offset:14336
	s_waitcnt lgkmcnt(0)
	v_mfma_f32_32x32x16_bf16 v[130:145], v[162:165], v[166:169], v[130:145]
	ds_read_b128 v[162:165], v182 offset:480
	ds_read_b128 v[166:169], v223 offset:15360
	s_waitcnt lgkmcnt(0)
	v_mfma_f32_32x32x16_bf16 v[146:161], v[162:165], v[166:169], v[146:161]
	ds_read_b128 v[162:165], v182 offset:512
	ds_read_b128 v[166:169], v223 offset:16384
	s_waitcnt lgkmcnt(0)
	v_mfma_f32_32x32x16_bf16 v[130:145], v[162:165], v[166:169], v[130:145]
	ds_read_b128 v[162:165], v182 offset:544
	ds_read_b128 v[166:169], v223 offset:17408
	s_waitcnt lgkmcnt(0)
	v_mfma_f32_32x32x16_bf16 v[146:161], v[162:165], v[166:169], v[146:161]
	s_nop 11
	v_pk_add_f32 v[146:147], v[130:131], v[146:147]
	v_pk_add_f32 v[132:133], v[132:133], v[148:149]
	v_max_f32_e32 v130, v146, v147
	v_pk_add_f32 v[134:135], v[134:135], v[150:151]
	v_max3_f32 v130, v130, v132, v133
	v_pk_add_f32 v[136:137], v[136:137], v[152:153]
	v_max3_f32 v130, v130, v134, v135
	v_pk_add_f32 v[138:139], v[138:139], v[154:155]
	v_max3_f32 v130, v130, v136, v137
	v_and_b32_e32 v131, 64, v218
	v_pk_add_f32 v[140:141], v[140:141], v[156:157]
	v_max3_f32 v130, v130, v138, v139
	v_xor_b32_e32 v149, 32, v218
	v_add_u32_e32 v150, 64, v131
	v_pk_add_f32 v[142:143], v[142:143], v[158:159]
	v_max3_f32 v130, v130, v140, v141
	v_cmp_lt_i32_e32 vcc, v149, v150
	v_pk_add_f32 v[144:145], v[144:145], v[160:161]
	v_max3_f32 v130, v130, v142, v143
	v_cndmask_b32_e32 v131, v218, v149, vcc
	v_max3_f32 v130, v130, v144, v145
	v_lshlrev_b32_e32 v131, 2, v131
	ds_bpermute_b32 v131, v131, v130
	s_waitcnt lgkmcnt(0)
	v_max3_f32 v148, v184, v130, v131
	v_sub_f32_e32 v130, v184, v148
	v_cmp_gt_f32_e32 vcc, 0xc2800000, v130
	s_cbranch_vccnz .Llazy2_full
	v_mov_b32_e32 v148, v184
	v_mov_b32_e32 v130, 1.0
	s_branch .LBB0_966

.LBB0_1005:
	s_nop 0
	v_max3_f32 v64, v171, v169, v52
	v_max3_f32 v65, v160, v59, v161
	v_max3_f32 v64, v64, v166, v53
	v_max3_f32 v65, v65, v60, v158
	v_max3_f32 v64, v64, v167, v168
	v_max3_f32 v65, v65, v61, v159
	v_max3_f32 v64, v64, v170, v54
	v_max3_f32 v65, v65, v62, v156
	v_max3_f32 v64, v64, v164, v55
	v_max3_f32 v65, v65, v63, v157
	v_max3_f32 v64, v64, v165, v56
	v_max3_f32 v65, v65, v50, v154
	v_max3_f32 v64, v64, v162, v57
	v_max3_f32 v65, v65, v51, v155
	v_max3_f32 v64, v64, v163, v58
	v_max_f32_e32 v64, v64, v65
	v_sub_f32_e32 v65, v181, v64
	v_cmp_gt_f32_e32 vcc, 0xc2800000, v65
	s_cbranch_vccnz .Llazy3_full
	s_waitcnt lgkmcnt(0)
	v_mov_b32_e32 v182, v181
	v_mov_b32_e32 v64, 1.0
	s_branch .LBB0_1007

.LBB0_1051:
	s_waitcnt lgkmcnt(0)
	s_nop 3
	s_nop 0
	v_max3_f32 v178, v99, v115, v100
	v_max3_f32 v179, v122, v107, v123
	v_max3_f32 v178, v178, v116, v101
	v_max3_f32 v179, v179, v108, v124
	v_max3_f32 v178, v178, v117, v114
	v_max3_f32 v179, v179, v109, v125
	v_max3_f32 v178, v178, v98, v102
	v_max3_f32 v179, v179, v110, v126
	v_max3_f32 v178, v178, v118, v103
	v_max3_f32 v179, v179, v111, v127
	v_max3_f32 v178, v178, v119, v104
	v_max3_f32 v179, v179, v112, v128
	v_max3_f32 v178, v178, v120, v105
	v_max3_f32 v179, v179, v113, v129
	v_max3_f32 v178, v178, v121, v106
	v_max_f32_e32 v178, v178, v179
	v_sub_f32_e32 v179, v205, v178
	v_cmp_gt_f32_e32 vcc, 0xc2800000, v179
	s_cbranch_vccnz .Llazy4_full
	s_waitcnt lgkmcnt(0)
	v_mov_b32_e32 v207, v205
	v_mov_b32_e32 v178, 1.0
	s_branch .LBB0_1053

.LBB0_1067:
	s_nop 3
	s_nop 0
	v_max3_f32 v114, v83, v67, v84
	v_max3_f32 v115, v74, v91, v75
	v_max3_f32 v114, v114, v68, v85
	v_max3_f32 v115, v115, v92, v76
	v_max3_f32 v114, v114, v69, v66
	v_max3_f32 v115, v115, v93, v77
	v_max3_f32 v114, v114, v82, v86
	v_max3_f32 v115, v115, v94, v78
	v_max3_f32 v114, v114, v70, v87
	v_max3_f32 v115, v115, v95, v79
	v_max3_f32 v114, v114, v71, v88
	v_max3_f32 v115, v115, v96, v80
	v_max3_f32 v114, v114, v72, v89
	v_max3_f32 v115, v115, v97, v81
	v_max3_f32 v114, v114, v73, v90
	v_max_f32_e32 v114, v114, v115
	v_sub_f32_e32 v115, v204, v114
	v_cmp_gt_f32_e32 vcc, 0xc2800000, v115
	s_cbranch_vccnz .Llazy5_full
	s_waitcnt lgkmcnt(0)
	v_mov_b32_e32 v206, v204
	v_mov_b32_e32 v114, 1.0
	s_branch .LBB0_1069

.LBB0_1107:
	s_waitcnt lgkmcnt(0)
	s_nop 3
	s_nop 0
	v_max3_f32 v178, v99, v115, v100
	v_max3_f32 v179, v122, v107, v123
	v_max3_f32 v178, v178, v116, v101
	v_max3_f32 v179, v179, v108, v124
	v_max3_f32 v178, v178, v117, v114
	v_max3_f32 v179, v179, v109, v125
	v_max3_f32 v178, v178, v98, v102
	v_max3_f32 v179, v179, v110, v126
	v_max3_f32 v178, v178, v118, v103
	v_max3_f32 v179, v179, v111, v127
	v_max3_f32 v178, v178, v119, v104
	v_max3_f32 v179, v179, v112, v128
	v_max3_f32 v178, v178, v120, v105
	v_max3_f32 v179, v179, v113, v129
	v_max3_f32 v178, v178, v121, v106
	v_max_f32_e32 v178, v178, v179
	v_sub_f32_e32 v179, v207, v178
	v_cmp_gt_f32_e32 vcc, 0xc2800000, v179
	s_cbranch_vccnz .Llazy6_full
	s_waitcnt lgkmcnt(0)
	v_mov_b32_e32 v205, v207
	v_mov_b32_e32 v178, 1.0
	s_branch .LBB0_1109

.LBB0_1124:
	s_nop 3
	s_nop 0
	v_max3_f32 v114, v83, v67, v84
	v_max3_f32 v115, v74, v91, v75
	v_max3_f32 v114, v114, v68, v85
	v_max3_f32 v115, v115, v92, v76
	v_max3_f32 v114, v114, v69, v66
	v_max3_f32 v115, v115, v93, v77
	v_max3_f32 v114, v114, v82, v86
	v_max3_f32 v115, v115, v94, v78
	v_max3_f32 v114, v114, v70, v87
	v_max3_f32 v115, v115, v95, v79
	v_max3_f32 v114, v114, v71, v88
	v_max3_f32 v115, v115, v96, v80
	v_max3_f32 v114, v114, v72, v89
	v_max3_f32 v115, v115, v97, v81
	v_max3_f32 v114, v114, v73, v90
	v_max_f32_e32 v114, v114, v115
	v_sub_f32_e32 v115, v206, v114
	v_cmp_gt_f32_e32 vcc, 0xc2800000, v115
	s_cbranch_vccnz .Llazy7_full
	s_waitcnt lgkmcnt(0)
	v_mov_b32_e32 v204, v206
	v_mov_b32_e32 v114, 1.0
	s_branch .LBB0_1126

.LBB0_1165:
	s_sub_i32 s45, s42, 64
	s_cmp_ge_u32 s45, s66
	s_cselect_b64 s[48:49], -1, 0
	s_cmp_gt_i32 s44, s39
	s_cselect_b64 s[50:51], -1, 0
	s_or_b64 s[48:49], s[50:51], s[48:49]
	s_and_b64 vcc, exec, s[48:49]
	s_cbranch_vccnz .LBB0_1169
	v_add_u32_e32 v120, v124, v198
	ds_read_b128 v[136:139], v120
	ds_read_b128 v[140:143], v120 offset:6656
	ds_read_b128 v[144:147], v120 offset:32
	ds_read_b128 v[148:151], v120 offset:6688
	ds_read_b128 v[152:155], v120 offset:64
	ds_read_b128 v[156:159], v120 offset:6720
	ds_read_b128 v[160:163], v120 offset:96
	ds_read_b128 v[164:167], v120 offset:6752
	ds_read_b128 v[168:171], v120 offset:128
	ds_read_b128 v[172:175], v120 offset:6784
	ds_read_b128 v[176:179], v120 offset:160
	ds_read_b128 v[180:183], v120 offset:6816
	v_add_u32_e32 v184, v125, v126
	s_waitcnt lgkmcnt(11)
	v_mfma_f32_32x32x16_bf16 v[34:49], v[136:139], v[66:69], v[220:235]
	s_waitcnt lgkmcnt(10)
	v_mfma_f32_32x32x16_bf16 v[50:65], v[140:143], v[66:69], v[220:235]
	s_waitcnt lgkmcnt(9)
	v_mfma_f32_32x32x16_bf16 v[34:49], v[144:147], v[70:73], v[34:49]
	s_waitcnt lgkmcnt(8)
	v_mfma_f32_32x32x16_bf16 v[50:65], v[148:151], v[70:73], v[50:65]
	s_waitcnt lgkmcnt(7)
	v_mfma_f32_32x32x16_bf16 v[34:49], v[152:155], v[74:77], v[34:49]
	s_waitcnt lgkmcnt(6)
	v_mfma_f32_32x32x16_bf16 v[50:65], v[156:159], v[74:77], v[50:65]
	s_waitcnt lgkmcnt(5)
	v_mfma_f32_32x32x16_bf16 v[34:49], v[160:163], v[78:81], v[34:49]
	s_waitcnt lgkmcnt(4)
	v_mfma_f32_32x32x16_bf16 v[50:65], v[164:167], v[78:81], v[50:65]
	s_waitcnt lgkmcnt(3)
	v_mfma_f32_32x32x16_bf16 v[34:49], v[168:171], v[106:109], v[34:49]
	s_waitcnt lgkmcnt(2)
	v_mfma_f32_32x32x16_bf16 v[50:65], v[172:175], v[106:109], v[50:65]
	s_waitcnt lgkmcnt(1)
	v_mfma_f32_32x32x16_bf16 v[34:49], v[176:179], v[110:113], v[34:49]
	s_waitcnt lgkmcnt(0)
	v_mfma_f32_32x32x16_bf16 v[50:65], v[180:183], v[110:113], v[50:65]
	s_nop 11
	v_max3_f32 v120, v34, v35, v36
	v_max3_f32 v130, v51, v52, v53
	v_max3_f32 v120, v120, v37, v38
	v_max3_f32 v130, v130, v54, v55
	v_max3_f32 v120, v120, v39, v40
	v_max3_f32 v130, v130, v56, v57
	v_max3_f32 v120, v120, v41, v42
	v_max3_f32 v130, v130, v58, v59
	v_max3_f32 v120, v120, v43, v44
	v_max3_f32 v130, v130, v60, v61
	v_max3_f32 v120, v120, v45, v46
	v_max3_f32 v130, v130, v62, v63
	v_max3_f32 v120, v120, v47, v48
	v_max3_f32 v130, v130, v64, v65
	v_max3_f32 v120, v120, v49, v50
	v_max_f32_e32 v120, v120, v130
	v_sub_f32_e32 v130, v236, v120
	v_cmp_gt_f32_e32 vcc, 0xc2800000, v130
	s_cbranch_vccnz .Llazy8_full
	ds_read_b64_tr_b16 v[136:137], v184 offset:13312
	ds_read_b64_tr_b16 v[138:139], v184 offset:14464
	ds_read_b64_tr_b16 v[140:141], v184 offset:13376
	ds_read_b64_tr_b16 v[142:143], v184 offset:14528
	ds_read_b64_tr_b16 v[144:145], v184 offset:15616
	ds_read_b64_tr_b16 v[146:147], v184 offset:16768
	ds_read_b64_tr_b16 v[148:149], v184 offset:15680
	ds_read_b64_tr_b16 v[150:151], v184 offset:16832
	ds_read_b64_tr_b16 v[152:153], v184 offset:17920
	ds_read_b64_tr_b16 v[154:155], v184 offset:19072
	ds_read_b64_tr_b16 v[156:157], v184 offset:17984
	ds_read_b64_tr_b16 v[158:159], v184 offset:19136
	ds_read_b64_tr_b16 v[160:161], v184 offset:20224
	ds_read_b64_tr_b16 v[162:163], v184 offset:21376
	ds_read_b64_tr_b16 v[164:165], v184 offset:20288
	ds_read_b64_tr_b16 v[166:167], v184 offset:21440
	v_mov_b32_e32 v130, v129
	v_mov_b32_e32 v120, 1.0
	s_branch .LBB0_1168

.LBB0_1179:
	s_cmp_ge_u32 s42, s66
	s_cselect_b64 s[48:49], -1, 0
	s_cmp_ge_i32 s44, s39
	s_cselect_b64 s[50:51], -1, 0
	s_or_b64 s[48:49], s[50:51], s[48:49]
	s_and_b64 vcc, exec, s[48:49]
	s_cbranch_vccnz .LBB0_1184
	v_add_u32_e32 v120, v124, v198
	ds_read_b128 v[136:139], v120 offset:32768
	ds_read_b128 v[140:143], v120 offset:39424
	ds_read_b128 v[144:147], v120 offset:32800
	ds_read_b128 v[148:151], v120 offset:39456
	ds_read_b128 v[152:155], v120 offset:32832
	ds_read_b128 v[156:159], v120 offset:39488
	ds_read_b128 v[160:163], v120 offset:32864
	ds_read_b128 v[164:167], v120 offset:39520
	ds_read_b128 v[168:171], v120 offset:32896
	ds_read_b128 v[172:175], v120 offset:39552
	ds_read_b128 v[176:179], v120 offset:32928
	ds_read_b128 v[180:183], v120 offset:39584
	v_add_u32_e32 v184, v125, v126
	s_waitcnt lgkmcnt(11)
	v_mfma_f32_32x32x16_bf16 v[34:49], v[136:139], v[66:69], v[220:235]
	s_waitcnt lgkmcnt(10)
	v_mfma_f32_32x32x16_bf16 v[50:65], v[140:143], v[66:69], v[220:235]
	s_waitcnt lgkmcnt(9)
	v_mfma_f32_32x32x16_bf16 v[34:49], v[144:147], v[70:73], v[34:49]
	s_waitcnt lgkmcnt(8)
	v_mfma_f32_32x32x16_bf16 v[50:65], v[148:151], v[70:73], v[50:65]
	s_waitcnt lgkmcnt(7)
	v_mfma_f32_32x32x16_bf16 v[34:49], v[152:155], v[74:77], v[34:49]
	s_waitcnt lgkmcnt(6)
	v_mfma_f32_32x32x16_bf16 v[50:65], v[156:159], v[74:77], v[50:65]
	s_waitcnt lgkmcnt(5)
	v_mfma_f32_32x32x16_bf16 v[34:49], v[160:163], v[78:81], v[34:49]
	s_waitcnt lgkmcnt(4)
	v_mfma_f32_32x32x16_bf16 v[50:65], v[164:167], v[78:81], v[50:65]
	s_waitcnt lgkmcnt(3)
	v_mfma_f32_32x32x16_bf16 v[34:49], v[168:171], v[106:109], v[34:49]
	s_waitcnt lgkmcnt(2)
	v_mfma_f32_32x32x16_bf16 v[50:65], v[172:175], v[106:109], v[50:65]
	s_waitcnt lgkmcnt(1)
	v_mfma_f32_32x32x16_bf16 v[34:49], v[176:179], v[110:113], v[34:49]
	s_waitcnt lgkmcnt(0)
	v_mfma_f32_32x32x16_bf16 v[50:65], v[180:183], v[110:113], v[50:65]
	s_nop 11
	v_max3_f32 v120, v34, v35, v36
	v_max3_f32 v129, v51, v52, v53
	v_max3_f32 v120, v120, v37, v38
	v_max3_f32 v129, v129, v54, v55
	v_max3_f32 v120, v120, v39, v40
	v_max3_f32 v129, v129, v56, v57
	v_max3_f32 v120, v120, v41, v42
	v_max3_f32 v129, v129, v58, v59
	v_max3_f32 v120, v120, v43, v44
	v_max3_f32 v129, v129, v60, v61
	v_max3_f32 v120, v120, v45, v46
	v_max3_f32 v129, v129, v62, v63
	v_max3_f32 v120, v120, v47, v48
	v_max3_f32 v129, v129, v64, v65
	v_max3_f32 v120, v120, v49, v50
	v_max_f32_e32 v120, v120, v129
	v_sub_f32_e32 v129, v236, v120
	v_cmp_gt_f32_e32 vcc, 0xc2800000, v129
	s_cbranch_vccnz .Llazy9_full
	ds_read_b64_tr_b16 v[136:137], v184 offset:46080
	ds_read_b64_tr_b16 v[138:139], v184 offset:47232
	ds_read_b64_tr_b16 v[140:141], v184 offset:46144
	ds_read_b64_tr_b16 v[142:143], v184 offset:47296
	ds_read_b64_tr_b16 v[144:145], v184 offset:48384
	ds_read_b64_tr_b16 v[146:147], v184 offset:49536
	ds_read_b64_tr_b16 v[148:149], v184 offset:48448
	ds_read_b64_tr_b16 v[150:151], v184 offset:49600
	ds_read_b64_tr_b16 v[152:153], v184 offset:50688
	ds_read_b64_tr_b16 v[154:155], v184 offset:51840
	ds_read_b64_tr_b16 v[156:157], v184 offset:50752
	ds_read_b64_tr_b16 v[158:159], v184 offset:51904
	ds_read_b64_tr_b16 v[160:161], v184 offset:52992
	ds_read_b64_tr_b16 v[162:163], v184 offset:54144
	ds_read_b64_tr_b16 v[164:165], v184 offset:53056
	ds_read_b64_tr_b16 v[166:167], v184 offset:54208
	v_mov_b32_e32 v129, v130
	v_mov_b32_e32 v120, 1.0
	s_branch .LBB0_1182
